# GEMM: accumulator zero-init with 64 v_mov_b64 instead of 2x128 v_mov_b32 (redundant second init removed)
# speedup vs baseline: 1.0081x; 1.0055x over previous
; __device__ __forceinline__ void gemm_phase(LAS unsigned char* lds, const Gemm g, const StaticOrder& S, const Epi& E, const int tid) {
;     ...
;     f32x4 acc[2][2][4][2];
; #pragma unroll
;     for (int a = 0; a < 2; ++a)
; #pragma unroll
;         for (int b = 0; b < 2; ++b)
; #pragma unroll
;             for (int m = 0; m < 4; ++m)
; #pragma unroll
;                 for (int n = 0; n < 2; ++n) acc[a][b][m][n] = (f32x4){0.f, 0.f, 0.f, 0.f};
;     ...
; #pragma unroll
;         for (int a = 0; a < 2; ++a)
; #pragma unroll
;             for (int b = 0; b < 2; ++b)
; #pragma unroll
;                 for (int m = 0; m < 4; ++m)
; #pragma unroll
;                     for (int n = 0; n < 2; ++n) acc[a][b][m][n] = (f32x4){0.f, 0.f, 0.f, 0.f};
.LBB0_528:
	v_readlane_b32 s18, v254, 62
	v_mov_b64_e32 v[2:3], 0
	v_mov_b64_e32 v[4:5], 0
	v_mov_b64_e32 v[6:7], 0
	v_mov_b64_e32 v[8:9], 0
	v_mov_b64_e32 v[10:11], 0
	v_mov_b64_e32 v[12:13], 0
	v_mov_b64_e32 v[14:15], 0
	v_mov_b64_e32 v[16:17], 0
	v_mov_b64_e32 v[18:19], 0
	v_mov_b64_e32 v[20:21], 0
	v_mov_b64_e32 v[22:23], 0
	v_mov_b64_e32 v[24:25], 0
	v_mov_b64_e32 v[26:27], 0
	v_mov_b64_e32 v[28:29], 0
	v_mov_b64_e32 v[30:31], 0
	v_mov_b64_e32 v[32:33], 0
	v_mov_b64_e32 v[34:35], 0
	v_mov_b64_e32 v[36:37], 0
	v_mov_b64_e32 v[38:39], 0
	v_mov_b64_e32 v[40:41], 0
	v_mov_b64_e32 v[42:43], 0
	v_mov_b64_e32 v[44:45], 0
	v_mov_b64_e32 v[46:47], 0
	v_mov_b64_e32 v[48:49], 0
	v_mov_b64_e32 v[50:51], 0
	v_mov_b64_e32 v[52:53], 0
	v_mov_b64_e32 v[54:55], 0
	v_mov_b64_e32 v[56:57], 0
	v_mov_b64_e32 v[58:59], 0
	v_mov_b64_e32 v[60:61], 0
	v_mov_b64_e32 v[62:63], 0
	v_mov_b64_e32 v[64:65], 0
	v_mov_b64_e32 v[66:67], 0
	v_mov_b64_e32 v[68:69], 0
	v_mov_b64_e32 v[70:71], 0
	v_mov_b64_e32 v[72:73], 0
	v_mov_b64_e32 v[74:75], 0
	v_mov_b64_e32 v[76:77], 0
	v_mov_b64_e32 v[78:79], 0
	v_mov_b64_e32 v[80:81], 0
	v_mov_b64_e32 v[82:83], 0
	v_mov_b64_e32 v[84:85], 0
	v_mov_b64_e32 v[86:87], 0
	v_mov_b64_e32 v[88:89], 0
	v_mov_b64_e32 v[90:91], 0
	v_mov_b64_e32 v[92:93], 0
	v_mov_b64_e32 v[94:95], 0
	v_mov_b64_e32 v[96:97], 0
	v_mov_b64_e32 v[98:99], 0
	v_mov_b64_e32 v[100:101], 0
	v_mov_b64_e32 v[102:103], 0
	v_mov_b64_e32 v[104:105], 0
	v_mov_b64_e32 v[106:107], 0
	v_mov_b64_e32 v[108:109], 0
	v_mov_b64_e32 v[110:111], 0
	v_mov_b64_e32 v[112:113], 0
	v_mov_b64_e32 v[114:115], 0
	v_mov_b64_e32 v[116:117], 0
	v_mov_b64_e32 v[118:119], 0
	v_mov_b64_e32 v[120:121], 0
	v_mov_b64_e32 v[122:123], 0
	v_mov_b64_e32 v[124:125], 0
	v_mov_b64_e32 v[126:127], 0
	v_mov_b64_e32 v[128:129], 0
	v_readlane_b32 s19, v254, 63
	s_andn2_b64 vcc, exec, s[18:19]
	s_cbranch_vccnz .LBB0_531
	s_add_u32 s2, s2, 0x80
	s_addc_u32 s3, s3, 0
	s_add_u32 s18, s4, 0x100
	s_addc_u32 s19, s5, 0
	s_mov_b32 s4, 0
